# attention running-max: 16-op v_max3 tree replaces 55-op canonicalising max tree in all 4 tile bodies
# speedup vs baseline: 1.0687x; 1.0060x over previous
; #define MFMA(a, b, c) __builtin_amdgcn_mfma_f32_32x32x16_f16((a), (b), (c), 0, 0, 0)
; template <int DK, bool MLA>
; DI void attn_item(const h16* __restrict__ Q, const h16* __restrict__ Kp, const h16* __restrict__ Kr, const h16* __restrict__ Vt,
;                   int kbeg, int kend, h16* __restrict__ out, h16* sm) {
;     ...
;     f32x16 st[2];
;     const float negm = -m;
; #pragma unroll
;     for (int i = 0; i < 16; ++i) { st[0][i] = negm; st[1][i] = negm; }
; #pragma unroll
;     for (int ks = 0; ks < DK / 16; ++ks) {
;       h16x8 k0 = *(const h16x8*)(ksm + r * KS + ks * 16 + hh * 8);
;       h16x8 k1 = *(const h16x8*)(ksm + (32 + r) * KS + ks * 16 + hh * 8);
;       st[0] = MFMA(k0, qf[ks], st[0]);
;       st[1] = MFMA(k1, qf[ks], st[1]);
;     }
;     float mx = fmaxf(st[0][0], st[1][0]);
; #pragma unroll
;     for (int i = 1; i < 16; ++i) mx = fmaxf(mx, fmaxf(st[0][i], st[1][i]));
;     mx = x32_max(mx);
;     if (__builtin_amdgcn_ballot_w64(mx > 8.f) != 0) {
.LBB0_2737:
	ds_read_b128 v[2:5], v141
	v_xor_b32_e32 v48, 0x80000000, v147
	v_mov_b32_e32 v49, v48
	v_mov_b32_e32 v50, v48
	v_mov_b32_e32 v51, v48
	v_mov_b32_e32 v52, v48
	v_mov_b32_e32 v53, v48
	v_mov_b32_e32 v54, v48
	v_mov_b32_e32 v55, v48
	v_mov_b32_e32 v56, v48
	v_mov_b32_e32 v57, v48
	v_mov_b32_e32 v58, v48
	v_mov_b32_e32 v59, v48
	v_mov_b32_e32 v60, v48
	v_mov_b32_e32 v61, v48
	v_mov_b32_e32 v62, v48
	v_mov_b32_e32 v63, v48
	s_waitcnt lgkmcnt(0)
	s_nop 0
	v_mfma_f32_32x32x16_f16 v[64:79], v[2:5], v[80:83], v[48:63]
	ds_read_b128 v[2:5], v141 offset:4608
	s_waitcnt lgkmcnt(0)
	v_mfma_f32_32x32x16_f16 v[48:63], v[2:5], v[80:83], v[48:63]
	ds_read_b128 v[2:5], v141 offset:32
	s_waitcnt lgkmcnt(0)
	v_mfma_f32_32x32x16_f16 v[64:79], v[2:5], v[84:87], v[64:79]
	ds_read_b128 v[2:5], v141 offset:4640
	s_waitcnt lgkmcnt(0)
	v_mfma_f32_32x32x16_f16 v[48:63], v[2:5], v[84:87], v[48:63]
	ds_read_b128 v[2:5], v141 offset:64
	s_waitcnt lgkmcnt(0)
	v_mfma_f32_32x32x16_f16 v[64:79], v[2:5], v[88:91], v[64:79]
	ds_read_b128 v[2:5], v141 offset:4672
	s_waitcnt lgkmcnt(0)
	v_mfma_f32_32x32x16_f16 v[48:63], v[2:5], v[88:91], v[48:63]
	ds_read_b128 v[2:5], v141 offset:4704
	s_waitcnt lgkmcnt(0)
	v_mfma_f32_32x32x16_f16 v[48:63], v[2:5], v[92:95], v[48:63]
	ds_read_b128 v[2:5], v141 offset:96
	s_waitcnt lgkmcnt(0)
	v_mfma_f32_32x32x16_f16 v[64:79], v[2:5], v[92:95], v[64:79]
	s_nop 8
	v_max3_f32 v0, v48, v49, v50
	v_max3_f32 v2, v51, v52, v53
	v_max3_f32 v3, v54, v55, v56
	v_max3_f32 v4, v57, v58, v59
	v_max3_f32 v0, v0, v60, v61
	v_max3_f32 v2, v2, v62, v63
	v_max3_f32 v3, v3, v64, v65
	v_max3_f32 v4, v4, v66, v67
	v_max3_f32 v0, v0, v68, v69
	v_max3_f32 v2, v2, v70, v71
	v_max3_f32 v3, v3, v72, v73
	v_max3_f32 v4, v4, v74, v75
	v_max3_f32 v0, v0, v76, v77
	v_max3_f32 v2, v2, v78, v79
	v_max3_f32 v0, v0, v2, v3
	v_max_f32_e32 v0, v0, v4
	v_mov_b32_e32 v2, v0
	s_nop 1
	v_permlane32_swap_b32_e32 v0, v2
	v_max_f32_e32 v2, v2, v2
	v_max_f32_e32 v0, v0, v0
	v_max_f32_e32 v0, v0, v2
	v_cmp_lt_f32_e32 vcc, s79, v0
	s_cbranch_vccz .LBB0_2739
	v_max_f32_e32 v0, v0, v0
	v_max_f32_e32 v0, 0, v0
	v_exp_f32_e64 v2, -v0
	v_add_f32_e32 v147, v147, v0
	v_pk_add_f32 v[64:65], v[64:65], v[0:1] op_sel_hi:[1,0] neg_lo:[0,1] neg_hi:[0,1]
	v_pk_add_f32 v[48:49], v[48:49], v[0:1] op_sel_hi:[1,0] neg_lo:[0,1] neg_hi:[0,1]
	v_mul_f32_e32 v153, v153, v2
	v_pk_add_f32 v[66:67], v[66:67], v[0:1] op_sel_hi:[1,0] neg_lo:[0,1] neg_hi:[0,1]
	v_pk_add_f32 v[50:51], v[50:51], v[0:1] op_sel_hi:[1,0] neg_lo:[0,1] neg_hi:[0,1]
	v_pk_add_f32 v[68:69], v[68:69], v[0:1] op_sel_hi:[1,0] neg_lo:[0,1] neg_hi:[0,1]
	v_pk_add_f32 v[52:53], v[52:53], v[0:1] op_sel_hi:[1,0] neg_lo:[0,1] neg_hi:[0,1]
	v_pk_add_f32 v[70:71], v[70:71], v[0:1] op_sel_hi:[1,0] neg_lo:[0,1] neg_hi:[0,1]
	v_pk_add_f32 v[54:55], v[54:55], v[0:1] op_sel_hi:[1,0] neg_lo:[0,1] neg_hi:[0,1]
	v_pk_add_f32 v[72:73], v[72:73], v[0:1] op_sel_hi:[1,0] neg_lo:[0,1] neg_hi:[0,1]
	v_pk_add_f32 v[56:57], v[56:57], v[0:1] op_sel_hi:[1,0] neg_lo:[0,1] neg_hi:[0,1]
	v_pk_add_f32 v[74:75], v[74:75], v[0:1] op_sel_hi:[1,0] neg_lo:[0,1] neg_hi:[0,1]
	v_pk_add_f32 v[58:59], v[58:59], v[0:1] op_sel_hi:[1,0] neg_lo:[0,1] neg_hi:[0,1]
	v_pk_add_f32 v[76:77], v[76:77], v[0:1] op_sel_hi:[1,0] neg_lo:[0,1] neg_hi:[0,1]
	v_pk_add_f32 v[60:61], v[60:61], v[0:1] op_sel_hi:[1,0] neg_lo:[0,1] neg_hi:[0,1]
	v_pk_mul_f32 v[46:47], v[46:47], v[2:3] op_sel_hi:[1,0]
	v_pk_mul_f32 v[44:45], v[44:45], v[2:3] op_sel_hi:[1,0]
	v_pk_mul_f32 v[42:43], v[42:43], v[2:3] op_sel_hi:[1,0]
	v_pk_mul_f32 v[40:41], v[40:41], v[2:3] op_sel_hi:[1,0]
	v_pk_mul_f32 v[38:39], v[38:39], v[2:3] op_sel_hi:[1,0]
	v_pk_mul_f32 v[36:37], v[36:37], v[2:3] op_sel_hi:[1,0]
	v_pk_mul_f32 v[34:35], v[34:35], v[2:3] op_sel_hi:[1,0]
	v_pk_mul_f32 v[32:33], v[32:33], v[2:3] op_sel_hi:[1,0]
	v_pk_mul_f32 v[30:31], v[30:31], v[2:3] op_sel_hi:[1,0]
	v_pk_mul_f32 v[28:29], v[28:29], v[2:3] op_sel_hi:[1,0]
	v_pk_mul_f32 v[26:27], v[26:27], v[2:3] op_sel_hi:[1,0]
	v_pk_mul_f32 v[24:25], v[24:25], v[2:3] op_sel_hi:[1,0]
	v_pk_mul_f32 v[22:23], v[22:23], v[2:3] op_sel_hi:[1,0]
	v_pk_mul_f32 v[20:21], v[20:21], v[2:3] op_sel_hi:[1,0]
	v_pk_mul_f32 v[18:19], v[18:19], v[2:3] op_sel_hi:[1,0]
	v_pk_mul_f32 v[16:17], v[16:17], v[2:3] op_sel_hi:[1,0]
	v_pk_add_f32 v[78:79], v[78:79], v[0:1] op_sel_hi:[1,0] neg_lo:[0,1] neg_hi:[0,1]
	v_pk_add_f32 v[62:63], v[62:63], v[0:1] op_sel_hi:[1,0] neg_lo:[0,1] neg_hi:[0,1]

; #define MFMA(a, b, c) __builtin_amdgcn_mfma_f32_32x32x16_f16((a), (b), (c), 0, 0, 0)
; template <int DK, bool MLA>
; DI void attn_item(const h16* __restrict__ Q, const h16* __restrict__ Kp, const h16* __restrict__ Kr, const h16* __restrict__ Vt,
;                   int kbeg, int kend, h16* __restrict__ out, h16* sm) {
;     ...
;     f32x16 st[2];
;     const float negm = -m;
; #pragma unroll
;     for (int i = 0; i < 16; ++i) { st[0][i] = negm; st[1][i] = negm; }
; #pragma unroll
;     for (int ks = 0; ks < DK / 16; ++ks) {
;       h16x8 k0 = *(const h16x8*)(ksm + r * KS + ks * 16 + hh * 8);
;       h16x8 k1 = *(const h16x8*)(ksm + (32 + r) * KS + ks * 16 + hh * 8);
;       st[0] = MFMA(k0, qf[ks], st[0]);
;       st[1] = MFMA(k1, qf[ks], st[1]);
;     }
;     float mx = fmaxf(st[0][0], st[1][0]);
; #pragma unroll
;     for (int i = 1; i < 16; ++i) mx = fmaxf(mx, fmaxf(st[0][i], st[1][i]));
;     mx = x32_max(mx);
;     if (__builtin_amdgcn_ballot_w64(mx > 8.f) != 0) {
;       const float dlt = fmaxf(mx, 0.f);
;       const float alpha = __builtin_amdgcn_exp2f(-dlt);
;       m += dlt;
;       lsum *= alpha;
; #pragma unroll
;       for (int i = 0; i < 16; ++i) { ot[0][i] *= alpha; ot[1][i] *= alpha; st[0][i] -= dlt; st[1][i] -= dlt; }
;     }
;     float ps = 0.f;
; #pragma unroll
;     for (int i = 0; i < 16; ++i) {
;       st[0][i] = __builtin_amdgcn_exp2f(st[0][i]);
;       st[1][i] = __builtin_amdgcn_exp2f(st[1][i]);
;       ps += st[0][i] + st[1][i];
;     }
;     lsum += ps;
.LBB0_2741:
	ds_read_b128 v[170:173], v141 offset:18432
	v_add_f32_e32 v166, v167, v166
	v_add_f32_e32 v166, 0, v166
	v_add_f32_e32 v13, v14, v13
	v_add_f32_e32 v13, v13, v166
	v_add_f32_e32 v14, v154, v15
	v_add_f32_e32 v13, v14, v13
	v_add_f32_e32 v14, v155, v152
	v_add_f32_e32 v13, v14, v13
	v_add_f32_e32 v14, v158, v156
	v_add_f32_e32 v13, v14, v13
	v_add_f32_e32 v14, v159, v157
	v_xor_b32_e32 v48, 0x80000000, v147
	v_add_f32_e32 v13, v14, v13
	v_add_f32_e32 v14, v169, v168
	v_mov_b32_e32 v49, v48
	v_mov_b32_e32 v50, v48
	v_mov_b32_e32 v51, v48
	v_mov_b32_e32 v52, v48
	v_mov_b32_e32 v53, v48
	v_mov_b32_e32 v54, v48
	v_mov_b32_e32 v55, v48
	v_mov_b32_e32 v56, v48
	v_mov_b32_e32 v57, v48
	v_mov_b32_e32 v58, v48
	v_mov_b32_e32 v59, v48
	v_mov_b32_e32 v60, v48
	v_mov_b32_e32 v61, v48
	v_mov_b32_e32 v62, v48
	v_mov_b32_e32 v63, v48
	v_add_f32_e32 v13, v14, v13
	v_add_f32_e32 v14, v163, v160
	v_add_f32_e32 v13, v14, v13
	v_add_f32_e32 v14, v164, v161
	ds_read_b128 v[158:161], v141 offset:18528
	s_waitcnt lgkmcnt(1)
	v_mfma_f32_32x32x16_f16 v[64:79], v[170:173], v[80:83], v[48:63]
	ds_read_b128 v[170:173], v141 offset:23040
	v_add_f32_e32 v13, v14, v13
	v_add_f32_e32 v14, v165, v162
	v_add_f32_e32 v13, v14, v13
	v_add_f32_e32 v7, v10, v7
	v_add_f32_e32 v7, v7, v13
	v_add_f32_e32 v8, v11, v8
	v_add_f32_e32 v7, v8, v7
	v_add_f32_e32 v8, v12, v9
	v_add_f32_e32 v7, v8, v7
	ds_read_b128 v[8:11], v141 offset:23136
	s_waitcnt lgkmcnt(1)
	v_mfma_f32_32x32x16_f16 v[48:63], v[170:173], v[80:83], v[48:63]
	ds_read_b128 v[170:173], v141 offset:18464
	ds_read_b128 v[174:177], v141 offset:23072
	ds_read_b128 v[154:157], v141 offset:23104
	v_add_f32_e32 v0, v4, v0
	v_add_f32_e32 v0, v0, v7
	v_add_f32_e32 v2, v5, v2
	v_add_f32_e32 v0, v2, v0
	s_waitcnt lgkmcnt(2)
	v_mfma_f32_32x32x16_f16 v[64:79], v[170:173], v[84:87], v[64:79]
	ds_read_b128 v[170:173], v141 offset:18496
	v_add_f32_e32 v2, v6, v3
	v_add_f32_e32 v0, v2, v0
	v_add_f32_e32 v0, v153, v0
	s_waitcnt lgkmcnt(2)
	v_mfma_f32_32x32x16_f16 v[48:63], v[174:177], v[84:87], v[48:63]
	s_waitcnt lgkmcnt(0)
	v_mfma_f32_32x32x16_f16 v[64:79], v[170:173], v[88:91], v[64:79]
	v_mfma_f32_32x32x16_f16 v[48:63], v[154:157], v[88:91], v[48:63]
	v_mfma_f32_32x32x16_f16 v[64:79], v[158:161], v[92:95], v[64:79]
	v_mfma_f32_32x32x16_f16 v[48:63], v[8:11], v[92:95], v[48:63]
	s_nop 10
	v_max3_f32 v2, v64, v65, v66
	v_max3_f32 v3, v67, v68, v69
	v_max3_f32 v4, v70, v71, v72
	v_max3_f32 v5, v73, v74, v75
	v_max3_f32 v2, v2, v76, v77
	v_max3_f32 v3, v3, v78, v79
	v_max3_f32 v4, v4, v48, v49
	v_max3_f32 v5, v5, v50, v51
	v_max3_f32 v2, v2, v52, v53
	v_max3_f32 v3, v3, v54, v55
	v_max3_f32 v4, v4, v56, v57
	v_max3_f32 v5, v5, v58, v59
	v_max3_f32 v2, v2, v60, v61
	v_max3_f32 v3, v3, v62, v63
	v_max3_f32 v2, v2, v3, v4
	v_max_f32_e32 v2, v2, v5
	v_mov_b32_e32 v3, v2
	s_nop 1
	v_permlane32_swap_b32_e32 v2, v3
	v_max_f32_e32 v3, v3, v3
	v_max_f32_e32 v2, v2, v2
	v_max_f32_e32 v2, v2, v3
	v_cmp_lt_f32_e32 vcc, s79, v2
	s_cbranch_vccz .LBB0_2734
	v_max_f32_e32 v2, v2, v2
	v_max_f32_e32 v2, 0, v2
	v_exp_f32_e64 v4, -v2
	v_add_f32_e32 v147, v147, v2
	v_pk_add_f32 v[64:65], v[64:65], v[2:3] op_sel_hi:[1,0] neg_lo:[0,1] neg_hi:[0,1]
	v_pk_add_f32 v[48:49], v[48:49], v[2:3] op_sel_hi:[1,0] neg_lo:[0,1] neg_hi:[0,1]
	v_mul_f32_e32 v0, v0, v4
	v_pk_add_f32 v[66:67], v[66:67], v[2:3] op_sel_hi:[1,0] neg_lo:[0,1] neg_hi:[0,1]
	v_pk_add_f32 v[50:51], v[50:51], v[2:3] op_sel_hi:[1,0] neg_lo:[0,1] neg_hi:[0,1]
	v_pk_add_f32 v[68:69], v[68:69], v[2:3] op_sel_hi:[1,0] neg_lo:[0,1] neg_hi:[0,1]
	v_pk_add_f32 v[52:53], v[52:53], v[2:3] op_sel_hi:[1,0] neg_lo:[0,1] neg_hi:[0,1]
	v_pk_add_f32 v[70:71], v[70:71], v[2:3] op_sel_hi:[1,0] neg_lo:[0,1] neg_hi:[0,1]
	v_pk_add_f32 v[54:55], v[54:55], v[2:3] op_sel_hi:[1,0] neg_lo:[0,1] neg_hi:[0,1]
	v_pk_add_f32 v[72:73], v[72:73], v[2:3] op_sel_hi:[1,0] neg_lo:[0,1] neg_hi:[0,1]
	v_pk_add_f32 v[56:57], v[56:57], v[2:3] op_sel_hi:[1,0] neg_lo:[0,1] neg_hi:[0,1]
	v_pk_add_f32 v[74:75], v[74:75], v[2:3] op_sel_hi:[1,0] neg_lo:[0,1] neg_hi:[0,1]
	v_pk_add_f32 v[58:59], v[58:59], v[2:3] op_sel_hi:[1,0] neg_lo:[0,1] neg_hi:[0,1]
	v_pk_add_f32 v[76:77], v[76:77], v[2:3] op_sel_hi:[1,0] neg_lo:[0,1] neg_hi:[0,1]
	v_pk_add_f32 v[60:61], v[60:61], v[2:3] op_sel_hi:[1,0] neg_lo:[0,1] neg_hi:[0,1]
	v_pk_mul_f32 v[46:47], v[46:47], v[4:5] op_sel_hi:[1,0]
	v_pk_mul_f32 v[44:45], v[44:45], v[4:5] op_sel_hi:[1,0]
	v_pk_mul_f32 v[42:43], v[42:43], v[4:5] op_sel_hi:[1,0]
	v_pk_mul_f32 v[40:41], v[40:41], v[4:5] op_sel_hi:[1,0]
	v_pk_mul_f32 v[38:39], v[38:39], v[4:5] op_sel_hi:[1,0]
	v_pk_mul_f32 v[36:37], v[36:37], v[4:5] op_sel_hi:[1,0]
	v_pk_mul_f32 v[34:35], v[34:35], v[4:5] op_sel_hi:[1,0]
	v_pk_mul_f32 v[32:33], v[32:33], v[4:5] op_sel_hi:[1,0]
	v_pk_mul_f32 v[30:31], v[30:31], v[4:5] op_sel_hi:[1,0]
	v_pk_mul_f32 v[28:29], v[28:29], v[4:5] op_sel_hi:[1,0]
	v_pk_mul_f32 v[26:27], v[26:27], v[4:5] op_sel_hi:[1,0]
	v_pk_mul_f32 v[24:25], v[24:25], v[4:5] op_sel_hi:[1,0]
	v_pk_mul_f32 v[22:23], v[22:23], v[4:5] op_sel_hi:[1,0]
	v_pk_mul_f32 v[20:21], v[20:21], v[4:5] op_sel_hi:[1,0]
	v_pk_mul_f32 v[18:19], v[18:19], v[4:5] op_sel_hi:[1,0]
	v_pk_mul_f32 v[16:17], v[16:17], v[4:5] op_sel_hi:[1,0]
	v_pk_add_f32 v[78:79], v[78:79], v[2:3] op_sel_hi:[1,0] neg_lo:[0,1] neg_hi:[0,1]
	v_pk_add_f32 v[62:63], v[62:63], v[2:3] op_sel_hi:[1,0] neg_lo:[0,1] neg_hi:[0,1]
	s_branch .LBB0_2734

; #define MFMA(a, b, c) __builtin_amdgcn_mfma_f32_32x32x16_f16((a), (b), (c), 0, 0, 0)
; template <int DK, bool MLA>
; DI void attn_item(const h16* __restrict__ Q, const h16* __restrict__ Kp, const h16* __restrict__ Kr, const h16* __restrict__ Vt,
;                   int kbeg, int kend, h16* __restrict__ out, h16* sm) {
;     ...
;     f32x16 st[2];
;     const float negm = -m;
; #pragma unroll
;     for (int i = 0; i < 16; ++i) { st[0][i] = negm; st[1][i] = negm; }
; #pragma unroll
;     for (int ks = 0; ks < DK / 16; ++ks) {
;       h16x8 k0 = *(const h16x8*)(ksm + r * KS + ks * 16 + hh * 8);
;       h16x8 k1 = *(const h16x8*)(ksm + (32 + r) * KS + ks * 16 + hh * 8);
;       st[0] = MFMA(k0, qf[ks], st[0]);
;       st[1] = MFMA(k1, qf[ks], st[1]);
;     }
;     float mx = fmaxf(st[0][0], st[1][0]);
; #pragma unroll
;     for (int i = 1; i < 16; ++i) mx = fmaxf(mx, fmaxf(st[0][i], st[1][i]));
;     mx = x32_max(mx);
;     if (__builtin_amdgcn_ballot_w64(mx > 8.f) != 0) {
.LBB0_2773:
	ds_read_b128 v[2:5], v163
	v_xor_b32_e32 v48, 0x80000000, v178
	v_mov_b32_e32 v49, v48
	v_mov_b32_e32 v50, v48
	v_mov_b32_e32 v51, v48
	v_mov_b32_e32 v52, v48
	v_mov_b32_e32 v53, v48
	v_mov_b32_e32 v54, v48
	v_mov_b32_e32 v55, v48
	v_mov_b32_e32 v56, v48
	v_mov_b32_e32 v57, v48
	v_mov_b32_e32 v58, v48
	v_mov_b32_e32 v59, v48
	v_mov_b32_e32 v60, v48
	v_mov_b32_e32 v61, v48
	v_mov_b32_e32 v62, v48
	v_mov_b32_e32 v63, v48
	s_waitcnt lgkmcnt(0)
	s_nop 0
	v_mfma_f32_32x32x16_f16 v[64:79], v[2:5], v[80:83], v[48:63]
	ds_read_b128 v[2:5], v163 offset:6656
	s_waitcnt lgkmcnt(0)
	v_mfma_f32_32x32x16_f16 v[48:63], v[2:5], v[80:83], v[48:63]
	ds_read_b128 v[2:5], v163 offset:32
	s_waitcnt lgkmcnt(0)
	v_mfma_f32_32x32x16_f16 v[64:79], v[2:5], v[84:87], v[64:79]
	ds_read_b128 v[2:5], v163 offset:6688
	s_waitcnt lgkmcnt(0)
	v_mfma_f32_32x32x16_f16 v[48:63], v[2:5], v[84:87], v[48:63]
	ds_read_b128 v[2:5], v163 offset:64
	s_waitcnt lgkmcnt(0)
	v_mfma_f32_32x32x16_f16 v[64:79], v[2:5], v[88:91], v[64:79]
	ds_read_b128 v[2:5], v163 offset:6720
	s_waitcnt lgkmcnt(0)
	v_mfma_f32_32x32x16_f16 v[48:63], v[2:5], v[88:91], v[48:63]
	ds_read_b128 v[2:5], v163 offset:96
	s_waitcnt lgkmcnt(0)
	v_mfma_f32_32x32x16_f16 v[64:79], v[2:5], v[92:95], v[64:79]
	ds_read_b128 v[2:5], v163 offset:6752
	s_waitcnt lgkmcnt(0)
	v_mfma_f32_32x32x16_f16 v[48:63], v[2:5], v[92:95], v[48:63]
	ds_read_b128 v[2:5], v163 offset:128
	s_waitcnt lgkmcnt(0)
	v_mfma_f32_32x32x16_f16 v[64:79], v[2:5], v[96:99], v[64:79]
	ds_read_b128 v[2:5], v163 offset:6784
	s_waitcnt lgkmcnt(0)
	v_mfma_f32_32x32x16_f16 v[48:63], v[2:5], v[96:99], v[48:63]
	ds_read_b128 v[2:5], v163 offset:6816
	s_waitcnt lgkmcnt(0)
	v_mfma_f32_32x32x16_f16 v[48:63], v[2:5], v[100:103], v[48:63]
	ds_read_b128 v[2:5], v163 offset:160
	s_waitcnt lgkmcnt(0)
	v_mfma_f32_32x32x16_f16 v[64:79], v[2:5], v[100:103], v[64:79]
	s_nop 8
	v_max3_f32 v0, v48, v49, v50
	v_max3_f32 v2, v51, v52, v53
	v_max3_f32 v3, v54, v55, v56
	v_max3_f32 v4, v57, v58, v59
	v_max3_f32 v0, v0, v60, v61
	v_max3_f32 v2, v2, v62, v63
	v_max3_f32 v3, v3, v64, v65
	v_max3_f32 v4, v4, v66, v67
	v_max3_f32 v0, v0, v68, v69
	v_max3_f32 v2, v2, v70, v71
	v_max3_f32 v3, v3, v72, v73
	v_max3_f32 v4, v4, v74, v75
	v_max3_f32 v0, v0, v76, v77
	v_max3_f32 v2, v2, v78, v79
	v_max3_f32 v0, v0, v2, v3
	v_max_f32_e32 v0, v0, v4
	v_mov_b32_e32 v2, v0
	s_nop 1
	v_permlane32_swap_b32_e32 v0, v2
	v_max_f32_e32 v2, v2, v2
	v_max_f32_e32 v0, v0, v0
	v_max_f32_e32 v0, v0, v2
	v_cmp_lt_f32_e32 vcc, s79, v0
	s_cbranch_vccz .LBB0_2775
	v_max_f32_e32 v0, v0, v0
	v_max_f32_e32 v0, 0, v0
	v_exp_f32_e64 v2, -v0
	v_add_f32_e32 v178, v178, v0
	v_pk_add_f32 v[64:65], v[64:65], v[0:1] op_sel_hi:[1,0] neg_lo:[0,1] neg_hi:[0,1]
	v_pk_add_f32 v[48:49], v[48:49], v[0:1] op_sel_hi:[1,0] neg_lo:[0,1] neg_hi:[0,1]
	v_mul_f32_e32 v153, v153, v2
	v_pk_add_f32 v[66:67], v[66:67], v[0:1] op_sel_hi:[1,0] neg_lo:[0,1] neg_hi:[0,1]
	v_pk_add_f32 v[50:51], v[50:51], v[0:1] op_sel_hi:[1,0] neg_lo:[0,1] neg_hi:[0,1]
	v_pk_add_f32 v[68:69], v[68:69], v[0:1] op_sel_hi:[1,0] neg_lo:[0,1] neg_hi:[0,1]
	v_pk_add_f32 v[52:53], v[52:53], v[0:1] op_sel_hi:[1,0] neg_lo:[0,1] neg_hi:[0,1]
	v_pk_add_f32 v[70:71], v[70:71], v[0:1] op_sel_hi:[1,0] neg_lo:[0,1] neg_hi:[0,1]
	v_pk_add_f32 v[54:55], v[54:55], v[0:1] op_sel_hi:[1,0] neg_lo:[0,1] neg_hi:[0,1]
	v_pk_add_f32 v[72:73], v[72:73], v[0:1] op_sel_hi:[1,0] neg_lo:[0,1] neg_hi:[0,1]
	v_pk_add_f32 v[56:57], v[56:57], v[0:1] op_sel_hi:[1,0] neg_lo:[0,1] neg_hi:[0,1]
	v_pk_add_f32 v[74:75], v[74:75], v[0:1] op_sel_hi:[1,0] neg_lo:[0,1] neg_hi:[0,1]
	v_pk_add_f32 v[58:59], v[58:59], v[0:1] op_sel_hi:[1,0] neg_lo:[0,1] neg_hi:[0,1]
	v_pk_add_f32 v[76:77], v[76:77], v[0:1] op_sel_hi:[1,0] neg_lo:[0,1] neg_hi:[0,1]
	v_pk_add_f32 v[60:61], v[60:61], v[0:1] op_sel_hi:[1,0] neg_lo:[0,1] neg_hi:[0,1]
	v_pk_mul_f32 v[46:47], v[46:47], v[2:3] op_sel_hi:[1,0]
	v_pk_mul_f32 v[44:45], v[44:45], v[2:3] op_sel_hi:[1,0]
	v_pk_mul_f32 v[42:43], v[42:43], v[2:3] op_sel_hi:[1,0]
	v_pk_mul_f32 v[40:41], v[40:41], v[2:3] op_sel_hi:[1,0]
	v_pk_mul_f32 v[38:39], v[38:39], v[2:3] op_sel_hi:[1,0]
	v_pk_mul_f32 v[36:37], v[36:37], v[2:3] op_sel_hi:[1,0]
	v_pk_mul_f32 v[34:35], v[34:35], v[2:3] op_sel_hi:[1,0]
	v_pk_mul_f32 v[32:33], v[32:33], v[2:3] op_sel_hi:[1,0]
	v_pk_mul_f32 v[30:31], v[30:31], v[2:3] op_sel_hi:[1,0]
	v_pk_mul_f32 v[28:29], v[28:29], v[2:3] op_sel_hi:[1,0]
	v_pk_mul_f32 v[26:27], v[26:27], v[2:3] op_sel_hi:[1,0]
	v_pk_mul_f32 v[24:25], v[24:25], v[2:3] op_sel_hi:[1,0]
	v_pk_mul_f32 v[22:23], v[22:23], v[2:3] op_sel_hi:[1,0]
	v_pk_mul_f32 v[20:21], v[20:21], v[2:3] op_sel_hi:[1,0]
	v_pk_mul_f32 v[18:19], v[18:19], v[2:3] op_sel_hi:[1,0]
	v_pk_mul_f32 v[16:17], v[16:17], v[2:3] op_sel_hi:[1,0]
	v_pk_add_f32 v[78:79], v[78:79], v[0:1] op_sel_hi:[1,0] neg_lo:[0,1] neg_hi:[0,1]
	v_pk_add_f32 v[62:63], v[62:63], v[0:1] op_sel_hi:[1,0] neg_lo:[0,1] neg_hi:[0,1]

; #define MFMA(a, b, c) __builtin_amdgcn_mfma_f32_32x32x16_f16((a), (b), (c), 0, 0, 0)
; template <int DK, bool MLA>
; DI void attn_item(const h16* __restrict__ Q, const h16* __restrict__ Kp, const h16* __restrict__ Kr, const h16* __restrict__ Vt,
;                   int kbeg, int kend, h16* __restrict__ out, h16* sm) {
;     ...
;     f32x16 st[2];
;     const float negm = -m;
; #pragma unroll
;     for (int i = 0; i < 16; ++i) { st[0][i] = negm; st[1][i] = negm; }
; #pragma unroll
;     for (int ks = 0; ks < DK / 16; ++ks) {
;       h16x8 k0 = *(const h16x8*)(ksm + r * KS + ks * 16 + hh * 8);
;       h16x8 k1 = *(const h16x8*)(ksm + (32 + r) * KS + ks * 16 + hh * 8);
;       st[0] = MFMA(k0, qf[ks], st[0]);
;       st[1] = MFMA(k1, qf[ks], st[1]);
;     }
;     float mx = fmaxf(st[0][0], st[1][0]);
; #pragma unroll
;     for (int i = 1; i < 16; ++i) mx = fmaxf(mx, fmaxf(st[0][i], st[1][i]));
;     mx = x32_max(mx);
;     if (__builtin_amdgcn_ballot_w64(mx > 8.f) != 0) {
;       const float dlt = fmaxf(mx, 0.f);
;       const float alpha = __builtin_amdgcn_exp2f(-dlt);
;       m += dlt;
;       lsum *= alpha;
; #pragma unroll
;       for (int i = 0; i < 16; ++i) { ot[0][i] *= alpha; ot[1][i] *= alpha; st[0][i] -= dlt; st[1][i] -= dlt; }
;     }
;     float ps = 0.f;
; #pragma unroll
;     for (int i = 0; i < 16; ++i) {
;       st[0][i] = __builtin_amdgcn_exp2f(st[0][i]);
;       st[1][i] = __builtin_amdgcn_exp2f(st[1][i]);
;       ps += st[0][i] + st[1][i];
;     }
;     lsum += ps;
.LBB0_2777:
	ds_read_b128 v[196:199], v163 offset:22528
	v_xor_b32_e32 v48, 0x80000000, v178
	v_mov_b32_e32 v49, v48
	v_mov_b32_e32 v50, v48
	v_mov_b32_e32 v51, v48
	v_mov_b32_e32 v52, v48
	v_mov_b32_e32 v53, v48
	v_mov_b32_e32 v54, v48
	v_mov_b32_e32 v55, v48
	v_mov_b32_e32 v56, v48
	v_mov_b32_e32 v57, v48
	v_mov_b32_e32 v58, v48
	v_mov_b32_e32 v59, v48
	v_mov_b32_e32 v60, v48
	v_mov_b32_e32 v61, v48
	v_mov_b32_e32 v62, v48
	v_mov_b32_e32 v63, v48
	v_add_f32_e32 v192, v194, v192
	v_add_f32_e32 v200, 0, v192
	v_add_f32_e32 v201, v195, v193
	ds_read_b128 v[192:195], v163 offset:29280
	s_waitcnt lgkmcnt(1)
	v_mfma_f32_32x32x16_f16 v[64:79], v[196:199], v[80:83], v[48:63]
	ds_read_b128 v[196:199], v163 offset:29184
	v_add_f32_e32 v5, v7, v5
	v_add_f32_e32 v6, v8, v6
	v_add_f32_e32 v0, v3, v0
	v_add_f32_e32 v2, v4, v2
	s_waitcnt lgkmcnt(0)
	v_mfma_f32_32x32x16_f16 v[48:63], v[196:199], v[80:83], v[48:63]
	ds_read_b128 v[196:199], v163 offset:22560
	s_waitcnt lgkmcnt(0)
	v_mfma_f32_32x32x16_f16 v[64:79], v[196:199], v[84:87], v[64:79]
	ds_read_b128 v[196:199], v163 offset:29216
	s_waitcnt lgkmcnt(0)
	v_mfma_f32_32x32x16_f16 v[48:63], v[196:199], v[84:87], v[48:63]
	ds_read_b128 v[196:199], v163 offset:22592
	s_waitcnt lgkmcnt(0)
	v_mfma_f32_32x32x16_f16 v[64:79], v[196:199], v[88:91], v[64:79]
	ds_read_b128 v[196:199], v163 offset:29248
	s_waitcnt lgkmcnt(0)
	v_mfma_f32_32x32x16_f16 v[48:63], v[196:199], v[88:91], v[48:63]
	ds_read_b128 v[196:199], v163 offset:22624
	s_waitcnt lgkmcnt(0)
	v_mfma_f32_32x32x16_f16 v[64:79], v[196:199], v[92:95], v[64:79]
	v_add_f32_e32 v196, v201, v200
	v_add_f32_e32 v5, v5, v196
	v_add_f32_e32 v5, v6, v5
	v_add_f32_e32 v6, v187, v186
	v_add_f32_e32 v5, v6, v5
	v_add_f32_e32 v6, v13, v9
	v_add_f32_e32 v5, v6, v5
	v_add_f32_e32 v6, v190, v188
	v_add_f32_e32 v5, v6, v5
	ds_read_b128 v[6:9], v163 offset:29312
	v_mfma_f32_32x32x16_f16 v[48:63], v[192:195], v[92:95], v[48:63]
	ds_read_b128 v[196:199], v163 offset:22656
	v_add_f32_e32 v13, v191, v189
	v_add_f32_e32 v5, v13, v5
	v_add_f32_e32 v13, v183, v180
	v_add_f32_e32 v5, v13, v5
	v_add_f32_e32 v13, v184, v181
	v_add_f32_e32 v5, v13, v5
	v_add_f32_e32 v13, v185, v182
	ds_read_b128 v[180:183], v163 offset:29344
	s_waitcnt lgkmcnt(2)
	v_mfma_f32_32x32x16_f16 v[48:63], v[6:9], v[96:99], v[48:63]
	v_add_f32_e32 v5, v13, v5
	v_add_f32_e32 v6, v14, v10
	v_add_f32_e32 v5, v6, v5
	v_add_f32_e32 v6, v15, v11
	v_add_f32_e32 v5, v6, v5
	ds_read_b128 v[6:9], v163 offset:22688
	v_add_f32_e32 v10, v179, v12
	s_waitcnt lgkmcnt(2)
	v_mfma_f32_32x32x16_f16 v[64:79], v[196:199], v[96:99], v[64:79]
	v_add_f32_e32 v5, v10, v5
	v_add_f32_e32 v0, v0, v5
	v_add_f32_e32 v0, v2, v0
	v_add_f32_e32 v0, v153, v0
	s_waitcnt lgkmcnt(1)
	v_mfma_f32_32x32x16_f16 v[48:63], v[180:183], v[100:103], v[48:63]
	s_waitcnt lgkmcnt(0)
	v_mfma_f32_32x32x16_f16 v[64:79], v[6:9], v[100:103], v[64:79]
	s_nop 9
	v_max3_f32 v2, v48, v49, v50
	v_max3_f32 v3, v51, v52, v53
	v_max3_f32 v4, v54, v55, v56
	v_max3_f32 v5, v57, v58, v59
	v_max3_f32 v2, v2, v60, v61
	v_max3_f32 v3, v3, v62, v63
	v_max3_f32 v4, v4, v64, v65
	v_max3_f32 v5, v5, v66, v67
	v_max3_f32 v2, v2, v68, v69
	v_max3_f32 v3, v3, v70, v71
	v_max3_f32 v4, v4, v72, v73
	v_max3_f32 v5, v5, v74, v75
	v_max3_f32 v2, v2, v76, v77
	v_max3_f32 v3, v3, v78, v79
	v_max3_f32 v2, v2, v3, v4
	v_max_f32_e32 v2, v2, v5
	v_mov_b32_e32 v3, v2
	s_nop 1
	v_permlane32_swap_b32_e32 v2, v3
	v_max_f32_e32 v3, v3, v3
	v_max_f32_e32 v2, v2, v2
	v_max_f32_e32 v2, v2, v3
	v_cmp_lt_f32_e32 vcc, s79, v2
	s_cbranch_vccz .LBB0_2770
	v_max_f32_e32 v2, v2, v2
	v_max_f32_e32 v2, 0, v2
	v_exp_f32_e64 v4, -v2
	v_add_f32_e32 v178, v178, v2
	v_pk_add_f32 v[64:65], v[64:65], v[2:3] op_sel_hi:[1,0] neg_lo:[0,1] neg_hi:[0,1]
	v_pk_add_f32 v[48:49], v[48:49], v[2:3] op_sel_hi:[1,0] neg_lo:[0,1] neg_hi:[0,1]
	v_mul_f32_e32 v0, v0, v4
	v_pk_add_f32 v[66:67], v[66:67], v[2:3] op_sel_hi:[1,0] neg_lo:[0,1] neg_hi:[0,1]
	v_pk_add_f32 v[50:51], v[50:51], v[2:3] op_sel_hi:[1,0] neg_lo:[0,1] neg_hi:[0,1]
	v_pk_add_f32 v[68:69], v[68:69], v[2:3] op_sel_hi:[1,0] neg_lo:[0,1] neg_hi:[0,1]
	v_pk_add_f32 v[52:53], v[52:53], v[2:3] op_sel_hi:[1,0] neg_lo:[0,1] neg_hi:[0,1]
	v_pk_add_f32 v[70:71], v[70:71], v[2:3] op_sel_hi:[1,0] neg_lo:[0,1] neg_hi:[0,1]
	v_pk_add_f32 v[54:55], v[54:55], v[2:3] op_sel_hi:[1,0] neg_lo:[0,1] neg_hi:[0,1]
	v_pk_add_f32 v[72:73], v[72:73], v[2:3] op_sel_hi:[1,0] neg_lo:[0,1] neg_hi:[0,1]
	v_pk_add_f32 v[56:57], v[56:57], v[2:3] op_sel_hi:[1,0] neg_lo:[0,1] neg_hi:[0,1]
	v_pk_add_f32 v[74:75], v[74:75], v[2:3] op_sel_hi:[1,0] neg_lo:[0,1] neg_hi:[0,1]
	v_pk_add_f32 v[58:59], v[58:59], v[2:3] op_sel_hi:[1,0] neg_lo:[0,1] neg_hi:[0,1]
	v_pk_add_f32 v[76:77], v[76:77], v[2:3] op_sel_hi:[1,0] neg_lo:[0,1] neg_hi:[0,1]
	v_pk_add_f32 v[60:61], v[60:61], v[2:3] op_sel_hi:[1,0] neg_lo:[0,1] neg_hi:[0,1]
	v_pk_mul_f32 v[46:47], v[46:47], v[4:5] op_sel_hi:[1,0]
	v_pk_mul_f32 v[44:45], v[44:45], v[4:5] op_sel_hi:[1,0]
	v_pk_mul_f32 v[42:43], v[42:43], v[4:5] op_sel_hi:[1,0]
	v_pk_mul_f32 v[40:41], v[40:41], v[4:5] op_sel_hi:[1,0]
	v_pk_mul_f32 v[38:39], v[38:39], v[4:5] op_sel_hi:[1,0]
	v_pk_mul_f32 v[36:37], v[36:37], v[4:5] op_sel_hi:[1,0]
	v_pk_mul_f32 v[34:35], v[34:35], v[4:5] op_sel_hi:[1,0]
	v_pk_mul_f32 v[32:33], v[32:33], v[4:5] op_sel_hi:[1,0]
	v_pk_mul_f32 v[30:31], v[30:31], v[4:5] op_sel_hi:[1,0]
	v_pk_mul_f32 v[28:29], v[28:29], v[4:5] op_sel_hi:[1,0]
	v_pk_mul_f32 v[26:27], v[26:27], v[4:5] op_sel_hi:[1,0]
	v_pk_mul_f32 v[24:25], v[24:25], v[4:5] op_sel_hi:[1,0]
	v_pk_mul_f32 v[22:23], v[22:23], v[4:5] op_sel_hi:[1,0]
	v_pk_mul_f32 v[20:21], v[20:21], v[4:5] op_sel_hi:[1,0]
	v_pk_mul_f32 v[18:19], v[18:19], v[4:5] op_sel_hi:[1,0]
	v_pk_mul_f32 v[16:17], v[16:17], v[4:5] op_sel_hi:[1,0]
	v_pk_add_f32 v[78:79], v[78:79], v[2:3] op_sel_hi:[1,0] neg_lo:[0,1] neg_hi:[0,1]
	v_pk_add_f32 v[62:63], v[62:63], v[2:3] op_sel_hi:[1,0] neg_lo:[0,1] neg_hi:[0,1]
	s_branch .LBB0_2770
